# first norm by hand with its x rows requested before the prep transposes and the first grid barrier (they wait in registers), so the cold input reads overlap the barrier
# speedup vs baseline: 1.0329x; 1.0097x over previous
.LBB0_30:
	s_or_b64 exec, exec, s[6:7]
	s_load_dwordx4 s[68:71], s[0:1], 0x0
	v_readfirstlane_b32 s65, v170
	v_and_b32_e32 v222, 63, v170
	v_lshlrev_b32_e32 v229, 4, v222
	s_lshr_b32 s65, s65, 6
	s_lshl_b32 s66, s2, 3
	s_add_i32 s66, s66, s65
	s_lshl_b32 s67, s66, 12
	s_waitcnt lgkmcnt(0)
	s_add_u32 s60, s68, s67
	s_addc_u32 s61, s69, 0
	global_load_dwordx4 v[96:99], v229, s[60:61] nt
	global_load_dwordx4 v[100:103], v229, s[60:61] offset:1024 nt
	global_load_dwordx4 v[104:107], v229, s[60:61] offset:2048 nt
	global_load_dwordx4 v[108:111], v229, s[60:61] offset:3072 nt
	s_add_u32 s60, s60, 0x800000
	s_addc_u32 s61, s61, 0
	global_load_dwordx4 v[112:115], v229, s[60:61] nt
	global_load_dwordx4 v[116:119], v229, s[60:61] offset:1024 nt
	global_load_dwordx4 v[120:123], v229, s[60:61] offset:2048 nt
	global_load_dwordx4 v[124:127], v229, s[60:61] offset:3072 nt
	s_add_u32 s60, s70, s67
	s_addc_u32 s61, s71, 0
	global_load_dwordx4 v[136:139], v229, s[60:61] nt
	global_load_dwordx4 v[140:143], v229, s[60:61] offset:1024 nt
	global_load_dwordx4 v[144:147], v229, s[60:61] offset:2048 nt
	global_load_dwordx4 v[148:151], v229, s[60:61] offset:3072 nt
	s_add_u32 s60, s60, 0x800000
	s_addc_u32 s61, s61, 0
	global_load_dwordx4 v[152:155], v229, s[60:61] nt
	global_load_dwordx4 v[156:159], v229, s[60:61] offset:1024 nt
	global_load_dwordx4 v[160:163], v229, s[60:61] offset:2048 nt
	global_load_dwordx4 v[164:167], v229, s[60:61] offset:3072 nt
	s_add_u32 s60, s60, 0x800000
	s_addc_u32 s61, s61, 0
	global_load_dwordx4 v[178:181], v229, s[60:61] nt
	global_load_dwordx4 v[182:185], v229, s[60:61] offset:1024 nt
	global_load_dwordx4 v[186:189], v229, s[60:61] offset:2048 nt
	global_load_dwordx4 v[190:193], v229, s[60:61] offset:3072 nt
	s_add_u32 s60, s60, 0x800000
	s_addc_u32 s61, s61, 0
	global_load_dwordx4 v[194:197], v229, s[60:61] nt
	global_load_dwordx4 v[198:201], v229, s[60:61] offset:1024 nt
	global_load_dwordx4 v[202:205], v229, s[60:61] offset:2048 nt
	global_load_dwordx4 v[206:209], v229, s[60:61] offset:3072 nt
	s_mov_b64 s[4:5], s[0:1]
	v_mov_b32_e32 v0, v170
	s_cmpk_gt_i32 s2, 0xdf
	s_cbranch_scc1 .LBB0_71
	s_load_dwordx2 s[6:7], s[4:5], 0xe8
	v_add_u32_e32 v4, 0x200, v0
	v_ashrrev_i32_e32 v11, 6, v4
	v_add_u32_e32 v4, 0x400, v0
	v_ashrrev_i32_e32 v12, 6, v4
	v_add_u32_e32 v4, 0x600, v0
	v_ashrrev_i32_e32 v13, 6, v4
	v_add_u32_e32 v4, 0x800, v0
	s_waitcnt lgkmcnt(0)
	s_add_u32 s8, s6, 0x780000
	v_ashrrev_i32_e32 v14, 6, v4
	v_add_u32_e32 v4, 0xa00, v0
	s_addc_u32 s9, s7, 0
	v_ashrrev_i32_e32 v15, 6, v4
	v_add_u32_e32 v4, 0xc00, v0
	s_add_u32 s3, s6, 0xe3c000
	v_ashrrev_i32_e32 v16, 6, v4
	v_add_u32_e32 v4, 0xe00, v0
	s_addc_u32 s30, s7, 0
	v_ashrrev_i32_e32 v17, 6, v4
	v_bfe_u32 v4, v0, 4, 2
	v_lshlrev_b32_e32 v5, 4, v0
	v_lshlrev_b32_e32 v3, 3, v0
	s_add_u32 s10, s6, 0xdbc000
	v_mul_u32_u24_e32 v4, 0x4100, v4
	v_and_b32_e32 v5, 0xf0, v5
	s_addc_u32 s11, s7, 0
	v_add3_u32 v5, 0, v4, v5
	v_and_b32_e32 v4, 56, v3
	s_add_u32 s12, s6, 0xbbc000
	v_ashrrev_i32_e32 v18, 3, v0
	v_mul_u32_u24_e32 v3, 0x41, v4
	v_ashrrev_i32_e32 v10, 6, v0
	v_lshlrev_b32_e32 v1, 2, v0
	s_addc_u32 s13, s7, 0
	s_movk_i32 s16, 0x104
	v_lshlrev_b32_e32 v20, 2, v18
	v_lshlrev_b32_e32 v3, 2, v3
	v_and_b32_e32 v2, 0xfc, v1
	s_add_u32 s14, s6, 0x7bc000
	v_mul_lo_u32 v6, v10, s16
	v_mul_lo_u32 v7, v11, s16
	v_mul_lo_u32 v8, v12, s16
	v_mul_lo_u32 v9, v13, s16
	v_mul_lo_u32 v26, v14, s16
	v_mul_lo_u32 v27, v15, s16
	v_mul_lo_u32 v28, v16, s16
	v_mul_lo_u32 v29, v17, s16
	v_add3_u32 v19, 0, v20, v3
	v_add3_u32 v20, 0, v3, v20
	s_addc_u32 s15, s7, 0
	v_mov_b32_e32 v1, 0
	s_mov_b32 s17, 0
	v_lshl_add_u32 v21, s2, 9, v0
	s_lshl_b32 s31, s42, 9
	v_lshlrev_b32_e32 v2, 2, v2
	v_add_u32_e32 v22, v5, v6
	v_add_u32_e32 v23, v5, v7
	v_add_u32_e32 v24, v5, v8
	v_add_u32_e32 v25, v5, v9
	v_add_u32_e32 v26, v5, v26
	v_add_u32_e32 v27, v5, v27
	v_add_u32_e32 v28, v5, v28
	v_add_u32_e32 v29, v5, v29
	v_lshlrev_b32_e32 v4, 1, v4
	s_mov_b32 s34, 0x88888889
	s_movk_i32 s35, 0x8800
	s_mov_b32 s36, 0x2aaaaaab
	s_movk_i32 s37, 0x6000
	s_movk_i32 s40, 0x3ff
	v_add_u32_e32 v30, 0x400, v19
	v_add_u32_e32 v31, 0x400, v20
	v_add_u32_e32 v32, 0x4000, v19
	v_add_u32_e32 v33, 0x4200, v20
	v_add_u32_e32 v34, 0x4400, v19
	v_add_u32_e32 v35, 0x4600, v20
	v_add_u32_e32 v36, 0x8200, v19
	v_add_u32_e32 v37, 0x8200, v20
	v_add_u32_e32 v38, 0x8600, v19
	v_add_u32_e32 v39, 0x8600, v20
	v_add_u32_e32 v40, 0xc200, v19
	v_add_u32_e32 v41, 0xc400, v20
	v_add_u32_e32 v42, 0xc600, v19
	v_add_u32_e32 v43, 0xc800, v20
	s_add_i32 s41, s2, 0x78
	s_branch .LBB0_34

.Lgs_noreset:
	s_lshl_b32 s46, s2, 3
	v_ashrrev_i32_e32 v0, 6, v2
	v_add_u32_e32 v3, s46, v0
	s_movk_i32 s3, 0x3000
	s_lshl_b32 s44, s42, 3
	v_cmp_gt_i32_e32 vcc, s3, v3
	v_mbcnt_lo_u32_b32 v135, -1, 0
	s_load_dwordx2 s[52:53], s[0:1], 0xe8
	v_mov_b32_e32 v231, 0x358637bd
	v_lshlrev_b32_e32 v230, 3, v222
	v_xor_b32_e32 v223, 32, v222
	v_xor_b32_e32 v224, 16, v222
	v_xor_b32_e32 v225, 8, v222
	v_xor_b32_e32 v226, 4, v222
	v_xor_b32_e32 v227, 2, v222
	v_xor_b32_e32 v228, 1, v222
	v_lshlrev_b32_e32 v223, 2, v223
	v_lshlrev_b32_e32 v224, 2, v224
	v_lshlrev_b32_e32 v225, 2, v225
	v_lshlrev_b32_e32 v226, 2, v226
	v_lshlrev_b32_e32 v227, 2, v227
	v_lshlrev_b32_e32 v228, 2, v228
	s_waitcnt lgkmcnt(0)
	s_add_u32 s58, s52, 0x780000
	s_addc_u32 s59, s53, 0
	s_add_u32 s60, s58, 0x0
	s_addc_u32 s61, s59, 0
	global_load_dwordx4 v[0:3], v229, s[60:61]
	global_load_dwordx4 v[4:7], v229, s[60:61] offset:1024
	global_load_dwordx4 v[8:11], v229, s[60:61] offset:2048
	global_load_dwordx4 v[12:15], v229, s[60:61] offset:3072
	s_add_u32 s60, s60, 0x1000
	s_addc_u32 s61, s61, 0
	global_load_dwordx4 v[16:19], v229, s[60:61]
	global_load_dwordx4 v[20:23], v229, s[60:61] offset:1024
	global_load_dwordx4 v[24:27], v229, s[60:61] offset:2048
	global_load_dwordx4 v[28:31], v229, s[60:61] offset:3072
	s_add_u32 s60, s58, 0x6000
	s_addc_u32 s61, s59, 0
	global_load_dwordx4 v[32:35], v229, s[60:61]
	global_load_dwordx4 v[36:39], v229, s[60:61] offset:1024
	global_load_dwordx4 v[40:43], v229, s[60:61] offset:2048
	global_load_dwordx4 v[44:47], v229, s[60:61] offset:3072
	s_add_u32 s60, s60, 0x1000
	s_addc_u32 s61, s61, 0
	global_load_dwordx4 v[48:51], v229, s[60:61]
	global_load_dwordx4 v[52:55], v229, s[60:61] offset:1024
	global_load_dwordx4 v[56:59], v229, s[60:61] offset:2048
	global_load_dwordx4 v[60:63], v229, s[60:61] offset:3072
	s_waitcnt vmcnt(36)
	v_mul_f32_e32 v210, v96, v96
	v_fmac_f32_e32 v210, v97, v97
	v_fmac_f32_e32 v210, v98, v98
	v_fmac_f32_e32 v210, v99, v99
	v_fmac_f32_e32 v210, v100, v100
	v_fmac_f32_e32 v210, v101, v101
	v_fmac_f32_e32 v210, v102, v102
	v_fmac_f32_e32 v210, v103, v103
	v_fmac_f32_e32 v210, v104, v104
	v_fmac_f32_e32 v210, v105, v105
	v_fmac_f32_e32 v210, v106, v106
	v_fmac_f32_e32 v210, v107, v107
	v_fmac_f32_e32 v210, v108, v108
	v_fmac_f32_e32 v210, v109, v109
	v_fmac_f32_e32 v210, v110, v110
	v_fmac_f32_e32 v210, v111, v111
	s_waitcnt vmcnt(32)
	v_mul_f32_e32 v212, v112, v112
	v_fmac_f32_e32 v212, v113, v113
	v_fmac_f32_e32 v212, v114, v114
	v_fmac_f32_e32 v212, v115, v115
	v_fmac_f32_e32 v212, v116, v116
	v_fmac_f32_e32 v212, v117, v117
	v_fmac_f32_e32 v212, v118, v118
	v_fmac_f32_e32 v212, v119, v119
	v_fmac_f32_e32 v212, v120, v120
	v_fmac_f32_e32 v212, v121, v121
	v_fmac_f32_e32 v212, v122, v122
	v_fmac_f32_e32 v212, v123, v123
	v_fmac_f32_e32 v212, v124, v124
	v_fmac_f32_e32 v212, v125, v125
	v_fmac_f32_e32 v212, v126, v126
	v_fmac_f32_e32 v212, v127, v127
	s_waitcnt vmcnt(28)
	v_mul_f32_e32 v214, v136, v136
	v_fmac_f32_e32 v214, v137, v137
	v_fmac_f32_e32 v214, v138, v138
	v_fmac_f32_e32 v214, v139, v139
	v_fmac_f32_e32 v214, v140, v140
	v_fmac_f32_e32 v214, v141, v141
	v_fmac_f32_e32 v214, v142, v142
	v_fmac_f32_e32 v214, v143, v143
	v_fmac_f32_e32 v214, v144, v144
	v_fmac_f32_e32 v214, v145, v145
	v_fmac_f32_e32 v214, v146, v146
	v_fmac_f32_e32 v214, v147, v147
	v_fmac_f32_e32 v214, v148, v148
	v_fmac_f32_e32 v214, v149, v149
	v_fmac_f32_e32 v214, v150, v150
	v_fmac_f32_e32 v214, v151, v151
	s_waitcnt vmcnt(24)
	v_mul_f32_e32 v216, v152, v152
	v_fmac_f32_e32 v216, v153, v153
	v_fmac_f32_e32 v216, v154, v154
	v_fmac_f32_e32 v216, v155, v155
	v_fmac_f32_e32 v216, v156, v156
	v_fmac_f32_e32 v216, v157, v157
	v_fmac_f32_e32 v216, v158, v158
	v_fmac_f32_e32 v216, v159, v159
	v_fmac_f32_e32 v216, v160, v160
	v_fmac_f32_e32 v216, v161, v161
	v_fmac_f32_e32 v216, v162, v162
	v_fmac_f32_e32 v216, v163, v163
	v_fmac_f32_e32 v216, v164, v164
	v_fmac_f32_e32 v216, v165, v165
	v_fmac_f32_e32 v216, v166, v166
	v_fmac_f32_e32 v216, v167, v167
	s_waitcnt vmcnt(20)
	v_mul_f32_e32 v218, v178, v178
	v_fmac_f32_e32 v218, v179, v179
	v_fmac_f32_e32 v218, v180, v180
	v_fmac_f32_e32 v218, v181, v181
	v_fmac_f32_e32 v218, v182, v182
	v_fmac_f32_e32 v218, v183, v183
	v_fmac_f32_e32 v218, v184, v184
	v_fmac_f32_e32 v218, v185, v185
	v_fmac_f32_e32 v218, v186, v186
	v_fmac_f32_e32 v218, v187, v187
	v_fmac_f32_e32 v218, v188, v188
	v_fmac_f32_e32 v218, v189, v189
	v_fmac_f32_e32 v218, v190, v190
	v_fmac_f32_e32 v218, v191, v191
	v_fmac_f32_e32 v218, v192, v192
	v_fmac_f32_e32 v218, v193, v193
	s_waitcnt vmcnt(16)
	v_mul_f32_e32 v220, v194, v194
	v_fmac_f32_e32 v220, v195, v195
	v_fmac_f32_e32 v220, v196, v196
	v_fmac_f32_e32 v220, v197, v197
	v_fmac_f32_e32 v220, v198, v198
	v_fmac_f32_e32 v220, v199, v199
	v_fmac_f32_e32 v220, v200, v200
	v_fmac_f32_e32 v220, v201, v201
	v_fmac_f32_e32 v220, v202, v202
	v_fmac_f32_e32 v220, v203, v203
	v_fmac_f32_e32 v220, v204, v204
	v_fmac_f32_e32 v220, v205, v205
	v_fmac_f32_e32 v220, v206, v206
	v_fmac_f32_e32 v220, v207, v207
	v_fmac_f32_e32 v220, v208, v208
	v_fmac_f32_e32 v220, v209, v209
	ds_bpermute_b32 v211, v223, v210
	ds_bpermute_b32 v213, v223, v212
	ds_bpermute_b32 v215, v223, v214
	ds_bpermute_b32 v217, v223, v216
	ds_bpermute_b32 v219, v223, v218
	ds_bpermute_b32 v221, v223, v220
	s_waitcnt lgkmcnt(5)
	v_add_f32_e32 v210, v210, v211
	s_waitcnt lgkmcnt(4)
	v_add_f32_e32 v212, v212, v213
	s_waitcnt lgkmcnt(3)
	v_add_f32_e32 v214, v214, v215
	s_waitcnt lgkmcnt(2)
	v_add_f32_e32 v216, v216, v217
	s_waitcnt lgkmcnt(1)
	v_add_f32_e32 v218, v218, v219
	s_waitcnt lgkmcnt(0)
	v_add_f32_e32 v220, v220, v221
	ds_bpermute_b32 v211, v224, v210
	ds_bpermute_b32 v213, v224, v212
	ds_bpermute_b32 v215, v224, v214
	ds_bpermute_b32 v217, v224, v216
	ds_bpermute_b32 v219, v224, v218
	ds_bpermute_b32 v221, v224, v220
	s_waitcnt lgkmcnt(5)
	v_add_f32_e32 v210, v210, v211
	s_waitcnt lgkmcnt(4)
	v_add_f32_e32 v212, v212, v213
	s_waitcnt lgkmcnt(3)
	v_add_f32_e32 v214, v214, v215
	s_waitcnt lgkmcnt(2)
	v_add_f32_e32 v216, v216, v217
	s_waitcnt lgkmcnt(1)
	v_add_f32_e32 v218, v218, v219
	s_waitcnt lgkmcnt(0)
	v_add_f32_e32 v220, v220, v221
	ds_bpermute_b32 v211, v225, v210
	ds_bpermute_b32 v213, v225, v212
	ds_bpermute_b32 v215, v225, v214
	ds_bpermute_b32 v217, v225, v216
	ds_bpermute_b32 v219, v225, v218
	ds_bpermute_b32 v221, v225, v220
	s_waitcnt lgkmcnt(5)
	v_add_f32_e32 v210, v210, v211
	s_waitcnt lgkmcnt(4)
	v_add_f32_e32 v212, v212, v213
	s_waitcnt lgkmcnt(3)
	v_add_f32_e32 v214, v214, v215
	s_waitcnt lgkmcnt(2)
	v_add_f32_e32 v216, v216, v217
	s_waitcnt lgkmcnt(1)
	v_add_f32_e32 v218, v218, v219
	s_waitcnt lgkmcnt(0)
	v_add_f32_e32 v220, v220, v221
	ds_bpermute_b32 v211, v226, v210
	ds_bpermute_b32 v213, v226, v212
	ds_bpermute_b32 v215, v226, v214
	ds_bpermute_b32 v217, v226, v216
	ds_bpermute_b32 v219, v226, v218
	ds_bpermute_b32 v221, v226, v220
	s_waitcnt lgkmcnt(5)
	v_add_f32_e32 v210, v210, v211
	s_waitcnt lgkmcnt(4)
	v_add_f32_e32 v212, v212, v213
	s_waitcnt lgkmcnt(3)
	v_add_f32_e32 v214, v214, v215
	s_waitcnt lgkmcnt(2)
	v_add_f32_e32 v216, v216, v217
	s_waitcnt lgkmcnt(1)
	v_add_f32_e32 v218, v218, v219
	s_waitcnt lgkmcnt(0)
	v_add_f32_e32 v220, v220, v221
	ds_bpermute_b32 v211, v227, v210
	ds_bpermute_b32 v213, v227, v212
	ds_bpermute_b32 v215, v227, v214
	ds_bpermute_b32 v217, v227, v216
	ds_bpermute_b32 v219, v227, v218
	ds_bpermute_b32 v221, v227, v220
	s_waitcnt lgkmcnt(5)
	v_add_f32_e32 v210, v210, v211
	s_waitcnt lgkmcnt(4)
	v_add_f32_e32 v212, v212, v213
	s_waitcnt lgkmcnt(3)
	v_add_f32_e32 v214, v214, v215
	s_waitcnt lgkmcnt(2)
	v_add_f32_e32 v216, v216, v217
	s_waitcnt lgkmcnt(1)
	v_add_f32_e32 v218, v218, v219
	s_waitcnt lgkmcnt(0)
	v_add_f32_e32 v220, v220, v221
	ds_bpermute_b32 v211, v228, v210
	ds_bpermute_b32 v213, v228, v212
	ds_bpermute_b32 v215, v228, v214
	ds_bpermute_b32 v217, v228, v216
	ds_bpermute_b32 v219, v228, v218
	ds_bpermute_b32 v221, v228, v220
	s_waitcnt lgkmcnt(5)
	v_add_f32_e32 v210, v210, v211
	s_waitcnt lgkmcnt(4)
	v_add_f32_e32 v212, v212, v213
	s_waitcnt lgkmcnt(3)
	v_add_f32_e32 v214, v214, v215
	s_waitcnt lgkmcnt(2)
	v_add_f32_e32 v216, v216, v217
	s_waitcnt lgkmcnt(1)
	v_add_f32_e32 v218, v218, v219
	s_waitcnt lgkmcnt(0)
	v_add_f32_e32 v220, v220, v221
	v_fmamk_f32 v210, v210, 0x3a800000, v231
	v_fmamk_f32 v212, v212, 0x3a800000, v231
	v_fmamk_f32 v214, v214, 0x3a800000, v231
	v_fmamk_f32 v216, v216, 0x3a800000, v231
	v_fmamk_f32 v218, v218, 0x3a800000, v231
	v_fmamk_f32 v220, v220, 0x3a800000, v231
	v_rsq_f32_e32 v210, v210
	v_rsq_f32_e32 v212, v212
	v_rsq_f32_e32 v214, v214
	v_rsq_f32_e32 v216, v216
	v_rsq_f32_e32 v218, v218
	v_rsq_f32_e32 v220, v220
	s_lshl_b32 s67, s66, 11
	s_add_u32 s56, s52, 0x2ebc000
	s_addc_u32 s57, s53, 0
	s_add_u32 s56, s56, s67
	s_addc_u32 s57, s57, 0
	s_waitcnt vmcnt(0)
	v_pk_mul_f32 v[96:97], v[96:97], v[210:211] op_sel_hi:[1,0]
	v_pk_mul_f32 v[98:99], v[98:99], v[210:211] op_sel_hi:[1,0]
	v_pk_fma_f32 v[96:97], v[96:97], v[0:1], v[16:17]
	v_pk_fma_f32 v[98:99], v[98:99], v[2:3], v[18:19]
	v_cvt_pk_bf16_f32 v96, v96, v97
	v_cvt_pk_bf16_f32 v97, v98, v99
	global_store_dwordx2 v230, v[96:97], s[56:57]
	v_pk_mul_f32 v[100:101], v[100:101], v[210:211] op_sel_hi:[1,0]
	v_pk_mul_f32 v[102:103], v[102:103], v[210:211] op_sel_hi:[1,0]
	v_pk_fma_f32 v[100:101], v[100:101], v[4:5], v[20:21]
	v_pk_fma_f32 v[102:103], v[102:103], v[6:7], v[22:23]
	v_cvt_pk_bf16_f32 v100, v100, v101
	v_cvt_pk_bf16_f32 v101, v102, v103
	global_store_dwordx2 v230, v[100:101], s[56:57] offset:512
	v_pk_mul_f32 v[104:105], v[104:105], v[210:211] op_sel_hi:[1,0]
	v_pk_mul_f32 v[106:107], v[106:107], v[210:211] op_sel_hi:[1,0]
	v_pk_fma_f32 v[104:105], v[104:105], v[8:9], v[24:25]
	v_pk_fma_f32 v[106:107], v[106:107], v[10:11], v[26:27]
	v_cvt_pk_bf16_f32 v104, v104, v105
	v_cvt_pk_bf16_f32 v105, v106, v107
	global_store_dwordx2 v230, v[104:105], s[56:57] offset:1024
	v_pk_mul_f32 v[108:109], v[108:109], v[210:211] op_sel_hi:[1,0]
	v_pk_mul_f32 v[110:111], v[110:111], v[210:211] op_sel_hi:[1,0]
	v_pk_fma_f32 v[108:109], v[108:109], v[12:13], v[28:29]
	v_pk_fma_f32 v[110:111], v[110:111], v[14:15], v[30:31]
	v_cvt_pk_bf16_f32 v108, v108, v109
	v_cvt_pk_bf16_f32 v109, v110, v111
	global_store_dwordx2 v230, v[108:109], s[56:57] offset:1536
	s_add_u32 s56, s56, 0x400000
	s_addc_u32 s57, s57, 0
	v_pk_mul_f32 v[112:113], v[112:113], v[212:213] op_sel_hi:[1,0]
	v_pk_mul_f32 v[114:115], v[114:115], v[212:213] op_sel_hi:[1,0]
	v_pk_fma_f32 v[112:113], v[112:113], v[0:1], v[16:17]
	v_pk_fma_f32 v[114:115], v[114:115], v[2:3], v[18:19]
	v_cvt_pk_bf16_f32 v112, v112, v113
	v_cvt_pk_bf16_f32 v113, v114, v115
	global_store_dwordx2 v230, v[112:113], s[56:57]
	v_pk_mul_f32 v[116:117], v[116:117], v[212:213] op_sel_hi:[1,0]
	v_pk_mul_f32 v[118:119], v[118:119], v[212:213] op_sel_hi:[1,0]
	v_pk_fma_f32 v[116:117], v[116:117], v[4:5], v[20:21]
	v_pk_fma_f32 v[118:119], v[118:119], v[6:7], v[22:23]
	v_cvt_pk_bf16_f32 v116, v116, v117
	v_cvt_pk_bf16_f32 v117, v118, v119
	global_store_dwordx2 v230, v[116:117], s[56:57] offset:512
	v_pk_mul_f32 v[120:121], v[120:121], v[212:213] op_sel_hi:[1,0]
	v_pk_mul_f32 v[122:123], v[122:123], v[212:213] op_sel_hi:[1,0]
	v_pk_fma_f32 v[120:121], v[120:121], v[8:9], v[24:25]
	v_pk_fma_f32 v[122:123], v[122:123], v[10:11], v[26:27]
	v_cvt_pk_bf16_f32 v120, v120, v121
	v_cvt_pk_bf16_f32 v121, v122, v123
	global_store_dwordx2 v230, v[120:121], s[56:57] offset:1024
	v_pk_mul_f32 v[124:125], v[124:125], v[212:213] op_sel_hi:[1,0]
	v_pk_mul_f32 v[126:127], v[126:127], v[212:213] op_sel_hi:[1,0]
	v_pk_fma_f32 v[124:125], v[124:125], v[12:13], v[28:29]
	v_pk_fma_f32 v[126:127], v[126:127], v[14:15], v[30:31]
	v_cvt_pk_bf16_f32 v124, v124, v125
	v_cvt_pk_bf16_f32 v125, v126, v127
	global_store_dwordx2 v230, v[124:125], s[56:57] offset:1536
	s_add_u32 s56, s56, 0x400000
	s_addc_u32 s57, s57, 0
	v_pk_mul_f32 v[136:137], v[136:137], v[214:215] op_sel_hi:[1,0]
	v_pk_mul_f32 v[138:139], v[138:139], v[214:215] op_sel_hi:[1,0]
	v_pk_fma_f32 v[136:137], v[136:137], v[32:33], v[48:49]
	v_pk_fma_f32 v[138:139], v[138:139], v[34:35], v[50:51]
	v_cvt_pk_bf16_f32 v136, v136, v137
	v_cvt_pk_bf16_f32 v137, v138, v139
	global_store_dwordx2 v230, v[136:137], s[56:57]
	v_pk_mul_f32 v[140:141], v[140:141], v[214:215] op_sel_hi:[1,0]
	v_pk_mul_f32 v[142:143], v[142:143], v[214:215] op_sel_hi:[1,0]
	v_pk_fma_f32 v[140:141], v[140:141], v[36:37], v[52:53]
	v_pk_fma_f32 v[142:143], v[142:143], v[38:39], v[54:55]
	v_cvt_pk_bf16_f32 v140, v140, v141
	v_cvt_pk_bf16_f32 v141, v142, v143
	global_store_dwordx2 v230, v[140:141], s[56:57] offset:512
	v_pk_mul_f32 v[144:145], v[144:145], v[214:215] op_sel_hi:[1,0]
	v_pk_mul_f32 v[146:147], v[146:147], v[214:215] op_sel_hi:[1,0]
	v_pk_fma_f32 v[144:145], v[144:145], v[40:41], v[56:57]
	v_pk_fma_f32 v[146:147], v[146:147], v[42:43], v[58:59]
	v_cvt_pk_bf16_f32 v144, v144, v145
	v_cvt_pk_bf16_f32 v145, v146, v147
	global_store_dwordx2 v230, v[144:145], s[56:57] offset:1024
	v_pk_mul_f32 v[148:149], v[148:149], v[214:215] op_sel_hi:[1,0]
	v_pk_mul_f32 v[150:151], v[150:151], v[214:215] op_sel_hi:[1,0]
	v_pk_fma_f32 v[148:149], v[148:149], v[44:45], v[60:61]
	v_pk_fma_f32 v[150:151], v[150:151], v[46:47], v[62:63]
	v_cvt_pk_bf16_f32 v148, v148, v149
	v_cvt_pk_bf16_f32 v149, v150, v151
	global_store_dwordx2 v230, v[148:149], s[56:57] offset:1536
	s_add_u32 s56, s56, 0x400000
	s_addc_u32 s57, s57, 0
	s_add_u32 s60, s58, 0xc000
	s_addc_u32 s61, s59, 0
	global_load_dwordx4 v[0:3], v229, s[60:61]
	global_load_dwordx4 v[4:7], v229, s[60:61] offset:1024
	global_load_dwordx4 v[8:11], v229, s[60:61] offset:2048
	global_load_dwordx4 v[12:15], v229, s[60:61] offset:3072
	s_add_u32 s60, s60, 0x1000
	s_addc_u32 s61, s61, 0
	global_load_dwordx4 v[16:19], v229, s[60:61]
	global_load_dwordx4 v[20:23], v229, s[60:61] offset:1024
	global_load_dwordx4 v[24:27], v229, s[60:61] offset:2048
	global_load_dwordx4 v[28:31], v229, s[60:61] offset:3072
	s_add_u32 s60, s58, 0x12000
	s_addc_u32 s61, s59, 0
	global_load_dwordx4 v[32:35], v229, s[60:61]
	global_load_dwordx4 v[36:39], v229, s[60:61] offset:1024
	global_load_dwordx4 v[40:43], v229, s[60:61] offset:2048
	global_load_dwordx4 v[44:47], v229, s[60:61] offset:3072
	s_add_u32 s60, s60, 0x1000
	s_addc_u32 s61, s61, 0
	global_load_dwordx4 v[48:51], v229, s[60:61]
	global_load_dwordx4 v[52:55], v229, s[60:61] offset:1024
	global_load_dwordx4 v[56:59], v229, s[60:61] offset:2048
	global_load_dwordx4 v[60:63], v229, s[60:61] offset:3072
	s_add_u32 s60, s58, 0x18000
	s_addc_u32 s61, s59, 0
	global_load_dwordx4 v[64:67], v229, s[60:61]
	global_load_dwordx4 v[68:71], v229, s[60:61] offset:1024
	global_load_dwordx4 v[72:75], v229, s[60:61] offset:2048
	global_load_dwordx4 v[76:79], v229, s[60:61] offset:3072
	s_add_u32 s60, s60, 0x1000
	s_addc_u32 s61, s61, 0
	global_load_dwordx4 v[80:83], v229, s[60:61]
	global_load_dwordx4 v[84:87], v229, s[60:61] offset:1024
	global_load_dwordx4 v[88:91], v229, s[60:61] offset:2048
	global_load_dwordx4 v[92:95], v229, s[60:61] offset:3072
	s_waitcnt vmcnt(16)
	v_pk_mul_f32 v[152:153], v[152:153], v[216:217] op_sel_hi:[1,0]
	v_pk_mul_f32 v[154:155], v[154:155], v[216:217] op_sel_hi:[1,0]
	v_pk_fma_f32 v[152:153], v[152:153], v[0:1], v[16:17]
	v_pk_fma_f32 v[154:155], v[154:155], v[2:3], v[18:19]
	v_cvt_pk_bf16_f32 v152, v152, v153
	v_cvt_pk_bf16_f32 v153, v154, v155
	global_store_dwordx2 v230, v[152:153], s[56:57]
	v_pk_mul_f32 v[156:157], v[156:157], v[216:217] op_sel_hi:[1,0]
	v_pk_mul_f32 v[158:159], v[158:159], v[216:217] op_sel_hi:[1,0]
	v_pk_fma_f32 v[156:157], v[156:157], v[4:5], v[20:21]
	v_pk_fma_f32 v[158:159], v[158:159], v[6:7], v[22:23]
	v_cvt_pk_bf16_f32 v156, v156, v157
	v_cvt_pk_bf16_f32 v157, v158, v159
	global_store_dwordx2 v230, v[156:157], s[56:57] offset:512
	v_pk_mul_f32 v[160:161], v[160:161], v[216:217] op_sel_hi:[1,0]
	v_pk_mul_f32 v[162:163], v[162:163], v[216:217] op_sel_hi:[1,0]
	v_pk_fma_f32 v[160:161], v[160:161], v[8:9], v[24:25]
	v_pk_fma_f32 v[162:163], v[162:163], v[10:11], v[26:27]
	v_cvt_pk_bf16_f32 v160, v160, v161
	v_cvt_pk_bf16_f32 v161, v162, v163
	global_store_dwordx2 v230, v[160:161], s[56:57] offset:1024
	v_pk_mul_f32 v[164:165], v[164:165], v[216:217] op_sel_hi:[1,0]
	v_pk_mul_f32 v[166:167], v[166:167], v[216:217] op_sel_hi:[1,0]
	v_pk_fma_f32 v[164:165], v[164:165], v[12:13], v[28:29]
	v_pk_fma_f32 v[166:167], v[166:167], v[14:15], v[30:31]
	v_cvt_pk_bf16_f32 v164, v164, v165
	v_cvt_pk_bf16_f32 v165, v166, v167
	global_store_dwordx2 v230, v[164:165], s[56:57] offset:1536
	s_add_u32 s56, s56, 0x400000
	s_addc_u32 s57, s57, 0
	s_waitcnt vmcnt(12)
	v_pk_mul_f32 v[178:179], v[178:179], v[218:219] op_sel_hi:[1,0]
	v_pk_mul_f32 v[180:181], v[180:181], v[218:219] op_sel_hi:[1,0]
	v_pk_fma_f32 v[178:179], v[178:179], v[32:33], v[48:49]
	v_pk_fma_f32 v[180:181], v[180:181], v[34:35], v[50:51]
	v_cvt_pk_bf16_f32 v178, v178, v179
	v_cvt_pk_bf16_f32 v179, v180, v181
	global_store_dwordx2 v230, v[178:179], s[56:57]
	v_pk_mul_f32 v[182:183], v[182:183], v[218:219] op_sel_hi:[1,0]
	v_pk_mul_f32 v[184:185], v[184:185], v[218:219] op_sel_hi:[1,0]
	v_pk_fma_f32 v[182:183], v[182:183], v[36:37], v[52:53]
	v_pk_fma_f32 v[184:185], v[184:185], v[38:39], v[54:55]
	v_cvt_pk_bf16_f32 v182, v182, v183
	v_cvt_pk_bf16_f32 v183, v184, v185
	global_store_dwordx2 v230, v[182:183], s[56:57] offset:512
	v_pk_mul_f32 v[186:187], v[186:187], v[218:219] op_sel_hi:[1,0]
	v_pk_mul_f32 v[188:189], v[188:189], v[218:219] op_sel_hi:[1,0]
	v_pk_fma_f32 v[186:187], v[186:187], v[40:41], v[56:57]
	v_pk_fma_f32 v[188:189], v[188:189], v[42:43], v[58:59]
	v_cvt_pk_bf16_f32 v186, v186, v187
	v_cvt_pk_bf16_f32 v187, v188, v189
	global_store_dwordx2 v230, v[186:187], s[56:57] offset:1024
	v_pk_mul_f32 v[190:191], v[190:191], v[218:219] op_sel_hi:[1,0]
	v_pk_mul_f32 v[192:193], v[192:193], v[218:219] op_sel_hi:[1,0]
	v_pk_fma_f32 v[190:191], v[190:191], v[44:45], v[60:61]
	v_pk_fma_f32 v[192:193], v[192:193], v[46:47], v[62:63]
	v_cvt_pk_bf16_f32 v190, v190, v191
	v_cvt_pk_bf16_f32 v191, v192, v193
	global_store_dwordx2 v230, v[190:191], s[56:57] offset:1536
	s_add_u32 s56, s56, 0x400000
	s_addc_u32 s57, s57, 0
	s_waitcnt vmcnt(8)
	v_pk_mul_f32 v[194:195], v[194:195], v[220:221] op_sel_hi:[1,0]
	v_pk_mul_f32 v[196:197], v[196:197], v[220:221] op_sel_hi:[1,0]
	v_pk_fma_f32 v[194:195], v[194:195], v[64:65], v[80:81]
	v_pk_fma_f32 v[196:197], v[196:197], v[66:67], v[82:83]
	v_cvt_pk_bf16_f32 v194, v194, v195
	v_cvt_pk_bf16_f32 v195, v196, v197
	global_store_dwordx2 v230, v[194:195], s[56:57]
	v_pk_mul_f32 v[198:199], v[198:199], v[220:221] op_sel_hi:[1,0]
	v_pk_mul_f32 v[200:201], v[200:201], v[220:221] op_sel_hi:[1,0]
	v_pk_fma_f32 v[198:199], v[198:199], v[68:69], v[84:85]
	v_pk_fma_f32 v[200:201], v[200:201], v[70:71], v[86:87]
	v_cvt_pk_bf16_f32 v198, v198, v199
	v_cvt_pk_bf16_f32 v199, v200, v201
	global_store_dwordx2 v230, v[198:199], s[56:57] offset:512
	v_pk_mul_f32 v[202:203], v[202:203], v[220:221] op_sel_hi:[1,0]
	v_pk_mul_f32 v[204:205], v[204:205], v[220:221] op_sel_hi:[1,0]
	v_pk_fma_f32 v[202:203], v[202:203], v[72:73], v[88:89]
	v_pk_fma_f32 v[204:205], v[204:205], v[74:75], v[90:91]
	v_cvt_pk_bf16_f32 v202, v202, v203
	v_cvt_pk_bf16_f32 v203, v204, v205
	global_store_dwordx2 v230, v[202:203], s[56:57] offset:1024
	v_pk_mul_f32 v[206:207], v[206:207], v[220:221] op_sel_hi:[1,0]
	v_pk_mul_f32 v[208:209], v[208:209], v[220:221] op_sel_hi:[1,0]
	v_pk_fma_f32 v[206:207], v[206:207], v[76:77], v[92:93]
	v_pk_fma_f32 v[208:209], v[208:209], v[78:79], v[94:95]
	v_cvt_pk_bf16_f32 v206, v206, v207
	v_cvt_pk_bf16_f32 v207, v208, v209
	global_store_dwordx2 v230, v[206:207], s[56:57] offset:1536
	s_add_u32 s56, s56, 0x400000
	s_addc_u32 s57, s57, 0
.LBB0_134:
	s_mov_b64 s[6:7], s[0:1]
	s_getreg_b32 s3, hwreg(HW_REG_XCC_ID, 0, 4)
	s_waitcnt vmcnt(0)
	s_waitcnt lgkmcnt(0)
	s_barrier
	s_and_saveexec_b64 s[4:5], s[38:39]
	s_cbranch_execz .LBB0_186
	s_and_b32 s20, s3, 15
	s_load_dwordx2 s[18:19], s[0:1], 0xe8
	s_add_i32 s98, s98, 1
	s_lshl_b32 s20, s20, 8
	v_mov_b32_e32 v0, 0
	v_mov_b32_e32 v1, 1
	s_waitcnt lgkmcnt(0)
	s_add_u32 s18, s18, 0x7798000
	s_addc_u32 s19, s19, 0
	s_add_u32 s24, s18, s20
	s_addc_u32 s25, s19, 0
	s_add_u32 s26, s24, 0x1400
	s_addc_u32 s27, s25, 0
	s_add_u32 s30, s24, 0x2400
	s_addc_u32 s31, s25, 0
	global_atomic_add v0, v1, s[26:27]
	s_cmp_lg_u32 s101, 0
	s_cbranch_scc1 .Lxbn1_fol
	s_mul_i32 s21, s98, s99
	s_mov_b32 s22, 0
